# skinny GEMM phases: all fragment loads issued up front with counted vmcnt waits (was vmcnt(0) after each small batch)
# speedup vs baseline: 1.0602x; 1.0602x over previous
; __device__ __forceinline__ f32x4 mfma16(bf16x8 a, bf16x8 b, f32x4 c) { return __builtin_amdgcn_mfma_f32_16x16x32_bf16(a, b, c, 0, 0, 0); }
; #define MFMA_SETTLE() do { __builtin_amdgcn_sched_barrier(0); asm volatile("s_nop 15\n\ts_nop 15" ::: "memory"); __builtin_amdgcn_sched_barrier(0); } while (0)
; template <int MODE>
; __device__ __forceinline__ void skinny_phase(const Params& P, unsigned char* shm) {
;     ...
;         const bf16_t* ap = A + (size_t)(ROW_S + 32 * mt + l16) * ld + k0 + 8 * q; const bf16_t* bp = Bt + (size_t)(32 * nt + l16) * ld + k0 + 8 * q;
;         f32x4 acc[2][2];
; #pragma unroll
;         for (int i = 0; i < 2; ++i) { acc[i][0] = (f32x4){0.f, 0.f, 0.f, 0.f}; acc[i][1] = (f32x4){0.f, 0.f, 0.f, 0.f}; }
; #pragma unroll 8
;         for (int ks = 0; ks < nks; ++ks) { const bf16x8 a0 = *(const bf16x8*)(ap + 32 * ks), a1 = *(const bf16x8*)(ap + (size_t)16 * ld + 32 * ks), b0 = *(const bf16x8*)(bp + 32 * ks), b1 = *(const bf16x8*)(bp + (size_t)16 * ld + 32 * ks);
;             acc[0][0] = mfma16(a0, b0, acc[0][0]); acc[0][1] = mfma16(a0, b1, acc[0][1]); acc[1][0] = mfma16(a1, b0, acc[1][0]); acc[1][1] = mfma16(a1, b1, acc[1][1]); }
;         MFMA_SETTLE();
; #pragma unroll
;         for (int mi = 0; mi < 2; ++mi)
; #pragma unroll
;             for (int ni = 0; ni < 2; ++ni)
; #pragma unroll
;                 for (int r = 0; r < 4; ++r) red[wave * 1024 + (16 * mi + 4 * q + r) * 32 + 16 * ni + l16] = acc[mi][ni][r];
;         __syncthreads();
;         { const int e = tid * 2, rr = e >> 5, cc = e & 31; const int row = ROW_S + 32 * mt + rr, col = 32 * nt + cc;
.LBB0_935:
	s_and_b32 s0, s4, 0x60
	s_or_b32 s17, s0, 0x2000
	v_or_b32_e32 v0, s17, v202
	v_lshlrev_b32_e32 v0, 11, v0
	s_and_b32 s18, s2, 0xffffffe0
	v_lshl_add_u64 v[58:59], v[2:3], 0, v[0:1]
	v_or_b32_e32 v18, s18, v202
	v_ashrrev_i32_e32 v19, 31, v18
	v_lshlrev_b64 v[18:19], 11, v[18:19]
	v_lshl_add_u64 v[60:61], v[4:5], 0, v[18:19]
	v_add_co_u32_e32 v62, vcc, s9, v58
	s_nop 1
	v_addc_co_u32_e32 v63, vcc, 0, v59, vcc
	v_add_co_u32_e32 v64, vcc, s9, v60
	s_nop 1
	v_addc_co_u32_e32 v65, vcc, 0, v61, vcc
	global_load_dwordx4 v[66:69], v[58:59], off
	global_load_dwordx4 v[70:73], v[60:61], off
	global_load_dwordx4 v[74:77], v[62:63], off
	global_load_dwordx4 v[78:81], v[64:65], off
	global_load_dwordx4 v[82:85], v[58:59], off offset:64
	global_load_dwordx4 v[86:89], v[60:61], off offset:64
	global_load_dwordx4 v[90:93], v[62:63], off offset:64
	global_load_dwordx4 v[94:97], v[64:65], off offset:64
	global_load_dwordx4 v[98:101], v[58:59], off offset:128
	global_load_dwordx4 v[102:105], v[60:61], off offset:128
	global_load_dwordx4 v[106:109], v[62:63], off offset:128
	global_load_dwordx4 v[110:113], v[64:65], off offset:128
	global_load_dwordx4 v[114:117], v[58:59], off offset:192
	global_load_dwordx4 v[118:121], v[60:61], off offset:192
	global_load_dwordx4 v[122:125], v[62:63], off offset:192
	global_load_dwordx4 v[128:131], v[64:65], off offset:192
	global_load_dwordx4 v[132:135], v[58:59], off offset:256
	global_load_dwordx4 v[136:139], v[60:61], off offset:256
	global_load_dwordx4 v[140:143], v[62:63], off offset:256
	global_load_dwordx4 v[144:147], v[64:65], off offset:256
	global_load_dwordx4 v[148:151], v[58:59], off offset:320
	global_load_dwordx4 v[152:155], v[60:61], off offset:320
	global_load_dwordx4 v[156:159], v[62:63], off offset:320
	global_load_dwordx4 v[160:163], v[64:65], off offset:320
	global_load_dwordx4 v[164:167], v[58:59], off offset:384
	global_load_dwordx4 v[168:171], v[60:61], off offset:384
	global_load_dwordx4 v[188:191], v[62:63], off offset:384
	global_load_dwordx4 v[192:195], v[64:65], off offset:384
	global_load_dwordx4 v[196:199], v[58:59], off offset:448
	global_load_dwordx4 v[30:33], v[60:61], off offset:448
	global_load_dwordx4 v[34:37], v[62:63], off offset:448
	global_load_dwordx4 v[38:41], v[64:65], off offset:448
	s_waitcnt vmcnt(28)
	v_mfma_f32_16x16x32_bf16 v[26:29], v[66:69], v[70:73], 0
	v_mfma_f32_16x16x32_bf16 v[14:17], v[66:69], v[78:81], 0
	v_mfma_f32_16x16x32_bf16 v[18:21], v[74:77], v[70:73], 0
	v_mfma_f32_16x16x32_bf16 v[22:25], v[74:77], v[78:81], 0
	s_waitcnt vmcnt(24)
	v_mfma_f32_16x16x32_bf16 v[26:29], v[82:85], v[86:89], v[26:29]
	v_mfma_f32_16x16x32_bf16 v[14:17], v[82:85], v[94:97], v[14:17]
	v_mfma_f32_16x16x32_bf16 v[18:21], v[90:93], v[86:89], v[18:21]
	v_mfma_f32_16x16x32_bf16 v[22:25], v[90:93], v[94:97], v[22:25]
	s_waitcnt vmcnt(20)
	v_mfma_f32_16x16x32_bf16 v[26:29], v[98:101], v[102:105], v[26:29]
	v_mfma_f32_16x16x32_bf16 v[14:17], v[98:101], v[110:113], v[14:17]
	v_mfma_f32_16x16x32_bf16 v[18:21], v[106:109], v[102:105], v[18:21]
	v_mfma_f32_16x16x32_bf16 v[22:25], v[106:109], v[110:113], v[22:25]
	s_waitcnt vmcnt(16)
	v_mfma_f32_16x16x32_bf16 v[26:29], v[114:117], v[118:121], v[26:29]
	v_mfma_f32_16x16x32_bf16 v[14:17], v[114:117], v[128:131], v[14:17]
	v_mfma_f32_16x16x32_bf16 v[18:21], v[122:125], v[118:121], v[18:21]
	v_mfma_f32_16x16x32_bf16 v[22:25], v[122:125], v[128:131], v[22:25]
	s_waitcnt vmcnt(12)
	v_mfma_f32_16x16x32_bf16 v[26:29], v[132:135], v[136:139], v[26:29]
	v_mfma_f32_16x16x32_bf16 v[14:17], v[132:135], v[144:147], v[14:17]
	v_mfma_f32_16x16x32_bf16 v[18:21], v[140:143], v[136:139], v[18:21]
	v_mfma_f32_16x16x32_bf16 v[22:25], v[140:143], v[144:147], v[22:25]
	s_waitcnt vmcnt(8)
	v_mfma_f32_16x16x32_bf16 v[26:29], v[148:151], v[152:155], v[26:29]
	v_mfma_f32_16x16x32_bf16 v[14:17], v[148:151], v[160:163], v[14:17]
	v_mfma_f32_16x16x32_bf16 v[18:21], v[156:159], v[152:155], v[18:21]
	v_mfma_f32_16x16x32_bf16 v[22:25], v[156:159], v[160:163], v[22:25]
	s_waitcnt vmcnt(4)
	v_mfma_f32_16x16x32_bf16 v[26:29], v[164:167], v[168:171], v[26:29]
	v_mfma_f32_16x16x32_bf16 v[14:17], v[164:167], v[192:195], v[14:17]
	v_mfma_f32_16x16x32_bf16 v[18:21], v[188:191], v[168:171], v[18:21]
	v_mfma_f32_16x16x32_bf16 v[22:25], v[188:191], v[192:195], v[22:25]
	s_waitcnt vmcnt(0)
	v_mfma_f32_16x16x32_bf16 v[26:29], v[196:199], v[30:33], v[26:29]
	v_mfma_f32_16x16x32_bf16 v[14:17], v[196:199], v[38:41], v[14:17]
	v_mfma_f32_16x16x32_bf16 v[18:21], v[34:37], v[30:33], v[18:21]
	v_mfma_f32_16x16x32_bf16 v[22:25], v[34:37], v[38:41], v[22:25]
	s_nop 15
	s_nop 15
	s_nop 4
	ds_write2_b32 v11, v26, v14 offset1:16
	ds_write2_b32 v11, v27, v15 offset0:32 offset1:48
	ds_write2_b32 v11, v28, v16 offset0:64 offset1:80
	ds_write2_b32 v11, v29, v17 offset0:96 offset1:112
	ds_write2_b32 v12, v18, v22 offset1:16
	ds_write2_b32 v12, v19, v23 offset0:32 offset1:48
	ds_write2_b32 v12, v20, v24 offset0:64 offset1:80
	ds_write2_b32 v12, v21, v25 offset0:96 offset1:112
	v_or_b32_e32 v14, s18, v9
	v_add_u32_e32 v0, s17, v8
	v_ashrrev_i32_e32 v15, 31, v14
	v_mad_u64_u32 v[16:17], s[0:1], v0, s10, v[6:7]
	v_lshlrev_b64 v[30:31], 1, v[14:15]
	v_lshl_add_u64 v[14:15], v[16:17], 0, v[30:31]
	v_add_co_u32_e32 v16, vcc, s8, v14
	s_waitcnt lgkmcnt(0)
	s_nop 0
	v_addc_co_u32_e32 v17, vcc, 0, v15, vcc
	v_add_co_u32_e32 v14, vcc, s11, v14
	s_barrier
; __device__ __forceinline__ unsigned cvt_pk_bf16(float lo, float hi) { unsigned r; asm volatile("v_cvt_pk_bf16_f32 %0, %1, %2" : "=v"(r) : "v"(lo), "v"(hi)); return r; }
; __device__ __forceinline__ float bflo(unsigned w) { return __uint_as_float(w << 16); }
; __device__ __forceinline__ float bfhi(unsigned w) { return __uint_as_float(w & 0xffff0000u); }
; __device__ __forceinline__ float sigmoidf_(float x) { return __builtin_amdgcn_rcpf(1.0f + __expf(-x)); }
; template <int MODE>
; __device__ __forceinline__ void skinny_phase(const Params& P, unsigned char* shm) {
;     ...
;         { const int e = tid * 2, rr = e >> 5, cc = e & 31; const int row = ROW_S + 32 * mt + rr, col = 32 * nt + cc;
;           float s0 = 0.f, s1 = 0.f, u0 = 0.f, u1 = 0.f;
; #pragma unroll
;           for (int w = 0; w < 4; ++w) { const f32x2 x = *(const f32x2*)(red + w * 1024 + e), y = *(const f32x2*)(red + (4 + w) * 1024 + e); s0 += x.x; s1 += x.y; u0 += y.x; u1 += y.y; }
;           if (MODE == 0) { const bf16_t* gp = (const bf16_t*)(ws + O_PROJ) + (size_t)row * NPROJ + col;
;               const unsigned ga = *(const unsigned*)(gp + C_GA), gb = *(const unsigned*)(gp + C_GB);
;               const float m0 = sigmoidf_(bflo(ga)) * s0 + sigmoidf_(bflo(gb)) * u0, m1 = sigmoidf_(bfhi(ga)) * s1 + sigmoidf_(bfhi(gb)) * u1;
;               *(unsigned*)((bf16_t*)(ws + O_MIX) + (size_t)row * D + col) = cvt_pk_bf16(m0, m1); }
	s_nop 0
	v_addc_co_u32_e32 v15, vcc, 0, v15, vcc
	global_load_dword v13, v[16:17], off offset:2048
	global_load_dword v40, v[14:15], off offset:2048
	ds_read2st64_b64 v[14:17], v10 offset1:8
	ds_read2st64_b64 v[18:21], v10 offset0:32 offset1:40
	ds_read2st64_b64 v[22:25], v10 offset0:16 offset1:24
	ds_read2st64_b64 v[26:29], v10 offset0:48 offset1:56
	v_lshlrev_b64 v[32:33], 12, v[0:1]
	v_lshl_add_u64 v[32:33], s[6:7], 0, v[32:33]
	v_lshl_add_u64 v[30:31], v[32:33], 0, v[30:31]
	s_waitcnt lgkmcnt(2)
	v_mov_b32_e32 v33, v18
	v_mov_b32_e32 v18, v15
	v_mov_b32_e32 v34, v16
	v_mov_b32_e32 v35, v20
	v_mov_b32_e32 v20, v17
	v_pk_add_f32 v[16:17], v[18:19], 0 op_sel_hi:[1,0]
	v_mov_b32_e32 v32, v14
	v_pk_add_f32 v[16:17], v[16:17], v[20:21]
	v_pk_add_f32 v[14:15], v[32:33], 0 op_sel_hi:[1,0]
	s_waitcnt lgkmcnt(1)
	v_mov_b32_e32 v36, v22
	s_waitcnt lgkmcnt(0)
	v_mov_b32_e32 v37, v26
	v_pk_add_f32 v[14:15], v[14:15], v[34:35]
	v_mov_b32_e32 v38, v24
	v_mov_b32_e32 v39, v28
	v_mov_b32_e32 v26, v23
	v_pk_add_f32 v[14:15], v[14:15], v[36:37]
	v_mov_b32_e32 v28, v25
	v_pk_add_f32 v[16:17], v[16:17], v[26:27]
	v_pk_add_f32 v[14:15], v[14:15], v[38:39]
	s_add_i32 s16, s16, s96
	s_add_i32 s2, s2, s3
	s_add_i32 s4, s4, s5
	v_pk_add_f32 v[16:17], v[16:17], v[28:29]
	s_cmpk_lt_i32 s16, 0x100
	s_waitcnt vmcnt(1)
	v_lshlrev_b32_e32 v0, 16, v13
	s_waitcnt vmcnt(0)
	v_lshlrev_b32_e32 v18, 16, v40
	v_and_b32_e32 v13, 0xffff0000, v13
	v_and_b32_e32 v19, 0xffff0000, v40
	v_mul_f32_e32 v0, 0xbfb8aa3b, v0
	v_mul_f32_e32 v18, 0xbfb8aa3b, v18
	v_mul_f32_e32 v13, 0xbfb8aa3b, v13
	v_mul_f32_e32 v19, 0xbfb8aa3b, v19
	v_exp_f32_e32 v0, v0
	v_exp_f32_e32 v18, v18
	v_exp_f32_e32 v13, v13
	v_exp_f32_e32 v19, v19
	v_add_f32_e32 v0, 1.0, v0
	v_add_f32_e32 v20, 1.0, v18
	v_add_f32_e32 v13, 1.0, v13
	v_add_f32_e32 v21, 1.0, v19
	v_rcp_f32_e32 v18, v0
	v_rcp_f32_e32 v19, v20
	v_rcp_f32_e32 v20, v13
	v_rcp_f32_e32 v21, v21
	v_pk_mul_f32 v[14:15], v[14:15], v[18:19]
	s_nop 0
	v_add_f32_e32 v0, v14, v15
	v_pk_mul_f32 v[16:17], v[16:17], v[20:21]
	s_nop 0
	v_add_f32_e32 v13, v16, v17
	v_cvt_pk_bf16_f32 v0, v0, v13
	global_store_dword v[30:31], v0, off
	s_barrier
	s_cbranch_scc1 .LBB0_935

; __device__ __forceinline__ float bflo(unsigned w) { return __uint_as_float(w << 16); }
; template <int MODE>
; __device__ __forceinline__ void skinny_phase(const Params& P, unsigned char* shm) {
;     ...
;         const bf16_t* ap = A + (size_t)(ROW_S + 32 * mt + l16) * ld + k0 + 8 * q; const bf16_t* bp = Bt + (size_t)(32 * nt + l16) * ld + k0 + 8 * q;
;         f32x4 acc[2][2];
; #pragma unroll
;         for (int i = 0; i < 2; ++i) { acc[i][0] = (f32x4){0.f, 0.f, 0.f, 0.f}; acc[i][1] = (f32x4){0.f, 0.f, 0.f, 0.f}; }
; #pragma unroll 8
;         for (int ks = 0; ks < nks; ++ks) { const bf16x8 a0 = *(const bf16x8*)(ap + 32 * ks), a1 = *(const bf16x8*)(ap + (size_t)16 * ld + 32 * ks), b0 = *(const bf16x8*)(bp + 32 * ks), b1 = *(const bf16x8*)(bp + (size_t)16 * ld + 32 * ks);
;             acc[0][0] = mfma16(a0, b0, acc[0][0]); acc[0][1] = mfma16(a0, b1, acc[0][1]); acc[1][0] = mfma16(a1, b0, acc[1][0]); acc[1][1] = mfma16(a1, b1, acc[1][1]); }
;         MFMA_SETTLE();
; #pragma unroll
;         for (int mi = 0; mi < 2; ++mi)
; #pragma unroll
;             for (int ni = 0; ni < 2; ++ni)
; #pragma unroll
;                 for (int r = 0; r < 4; ++r) red[wave * 1024 + (16 * mi + 4 * q + r) * 32 + 16 * ni + l16] = acc[mi][ni][r];
;         __syncthreads();
;         { const int e = tid * 2, rr = e >> 5, cc = e & 31; const int row = ROW_S + 32 * mt + rr, col = 32 * nt + cc;
;           float s0 = 0.f, s1 = 0.f, u0 = 0.f, u1 = 0.f;
; #pragma unroll
;           for (int w = 0; w < 4; ++w) { const f32x2 x = *(const f32x2*)(red + w * 1024 + e), y = *(const f32x2*)(red + (4 + w) * 1024 + e); s0 += x.x; s1 += x.y; u0 += y.x; u1 += y.y; }
;           if (MODE == 0) { const bf16_t* gp = (const bf16_t*)(ws + O_PROJ) + (size_t)row * NPROJ + col;
;               const unsigned ga = *(const unsigned*)(gp + C_GA), gb = *(const unsigned*)(gp + C_GB);
;               const float m0 = sigmoidf_(bflo(ga)) * s0 + sigmoidf_(bflo(gb)) * u0, m1 = sigmoidf_(bfhi(ga)) * s1 + sigmoidf_(bfhi(gb)) * u1;
;               *(unsigned*)((bf16_t*)(ws + O_MIX) + (size_t)row * D + col) = cvt_pk_bf16(m0, m1); }
;           else if (MODE == 1) { const f32x2 xv = *(const f32x2*)(P.in[1] + (size_t)(row - ROW_S) * D + col);
;               *(unsigned*)((bf16_t*)(ws + O_R) + (size_t)row * D + col) = cvt_pk_bf16(ALPHA * xv.x + s0 + u0, ALPHA * xv.y + s1 + u1); }
.LBB0_1025:
	s_and_b32 s0, s6, 0x60
	s_or_b32 s11, s0, 0x2000
	v_or_b32_e32 v0, s11, v206
	v_lshlrev_b32_e32 v0, 12, v0
	s_and_b32 s16, s2, 0xffffffe0
	v_lshl_add_u64 v[56:57], v[2:3], 0, v[0:1]
	v_or_b32_e32 v16, s16, v206
	v_ashrrev_i32_e32 v17, 31, v16
	v_lshlrev_b64 v[16:17], 12, v[16:17]
	v_lshl_add_u64 v[58:59], v[4:5], 0, v[16:17]
	v_add_co_u32_e32 v60, vcc, s8, v56
	s_nop 1
	v_addc_co_u32_e32 v61, vcc, 0, v57, vcc
	v_add_co_u32_e32 v62, vcc, s8, v58
	s_nop 1
	v_addc_co_u32_e32 v63, vcc, 0, v59, vcc
	global_load_dwordx4 v[66:69], v[56:57], off
	global_load_dwordx4 v[70:73], v[58:59], off
	global_load_dwordx4 v[74:77], v[60:61], off
	global_load_dwordx4 v[78:81], v[62:63], off
	global_load_dwordx4 v[82:85], v[56:57], off offset:64
	global_load_dwordx4 v[86:89], v[58:59], off offset:64
	global_load_dwordx4 v[90:93], v[60:61], off offset:64
	global_load_dwordx4 v[94:97], v[62:63], off offset:64
	global_load_dwordx4 v[98:101], v[56:57], off offset:128
	global_load_dwordx4 v[102:105], v[58:59], off offset:128
	global_load_dwordx4 v[106:109], v[60:61], off offset:128
	global_load_dwordx4 v[110:113], v[62:63], off offset:128
	global_load_dwordx4 v[114:117], v[56:57], off offset:192
	global_load_dwordx4 v[118:121], v[58:59], off offset:192
	global_load_dwordx4 v[122:125], v[60:61], off offset:192
	global_load_dwordx4 v[128:131], v[62:63], off offset:192
	global_load_dwordx4 v[132:135], v[56:57], off offset:256
	global_load_dwordx4 v[136:139], v[58:59], off offset:256
	global_load_dwordx4 v[140:143], v[60:61], off offset:256
	global_load_dwordx4 v[144:147], v[62:63], off offset:256
	global_load_dwordx4 v[148:151], v[56:57], off offset:320
	global_load_dwordx4 v[152:155], v[58:59], off offset:320
	global_load_dwordx4 v[156:159], v[60:61], off offset:320
	global_load_dwordx4 v[160:163], v[62:63], off offset:320
	global_load_dwordx4 v[164:167], v[56:57], off offset:384
	global_load_dwordx4 v[168:171], v[58:59], off offset:384
	global_load_dwordx4 v[172:175], v[60:61], off offset:384
	global_load_dwordx4 v[194:197], v[62:63], off offset:384
	global_load_dwordx4 v[198:201], v[56:57], off offset:448
	global_load_dwordx4 v[28:31], v[58:59], off offset:448
	global_load_dwordx4 v[32:35], v[60:61], off offset:448
	global_load_dwordx4 v[36:39], v[62:63], off offset:448
	s_waitcnt vmcnt(28)
	v_mfma_f32_16x16x32_bf16 v[24:27], v[66:69], v[70:73], 0
	v_mfma_f32_16x16x32_bf16 v[12:15], v[66:69], v[78:81], 0
	v_mfma_f32_16x16x32_bf16 v[16:19], v[74:77], v[70:73], 0
	v_mfma_f32_16x16x32_bf16 v[20:23], v[74:77], v[78:81], 0
	s_waitcnt vmcnt(24)
	v_mfma_f32_16x16x32_bf16 v[24:27], v[82:85], v[86:89], v[24:27]
	v_mfma_f32_16x16x32_bf16 v[12:15], v[82:85], v[94:97], v[12:15]
	v_mfma_f32_16x16x32_bf16 v[16:19], v[90:93], v[86:89], v[16:19]
	v_mfma_f32_16x16x32_bf16 v[20:23], v[90:93], v[94:97], v[20:23]
	s_waitcnt vmcnt(20)
	v_mfma_f32_16x16x32_bf16 v[24:27], v[98:101], v[102:105], v[24:27]
	v_mfma_f32_16x16x32_bf16 v[12:15], v[98:101], v[110:113], v[12:15]
	v_mfma_f32_16x16x32_bf16 v[16:19], v[106:109], v[102:105], v[16:19]
	v_mfma_f32_16x16x32_bf16 v[20:23], v[106:109], v[110:113], v[20:23]
	s_waitcnt vmcnt(16)
	v_mfma_f32_16x16x32_bf16 v[24:27], v[114:117], v[118:121], v[24:27]
	v_mfma_f32_16x16x32_bf16 v[12:15], v[114:117], v[128:131], v[12:15]
	v_mfma_f32_16x16x32_bf16 v[16:19], v[122:125], v[118:121], v[16:19]
	v_mfma_f32_16x16x32_bf16 v[20:23], v[122:125], v[128:131], v[20:23]
	s_waitcnt vmcnt(12)
	v_mfma_f32_16x16x32_bf16 v[24:27], v[132:135], v[136:139], v[24:27]
	v_mfma_f32_16x16x32_bf16 v[12:15], v[132:135], v[144:147], v[12:15]
	v_mfma_f32_16x16x32_bf16 v[16:19], v[140:143], v[136:139], v[16:19]
	v_mfma_f32_16x16x32_bf16 v[20:23], v[140:143], v[144:147], v[20:23]
	s_waitcnt vmcnt(8)
	v_mfma_f32_16x16x32_bf16 v[24:27], v[148:151], v[152:155], v[24:27]
	v_mfma_f32_16x16x32_bf16 v[12:15], v[148:151], v[160:163], v[12:15]
	v_mfma_f32_16x16x32_bf16 v[16:19], v[156:159], v[152:155], v[16:19]
	v_mfma_f32_16x16x32_bf16 v[20:23], v[156:159], v[160:163], v[20:23]
	s_waitcnt vmcnt(4)
	v_mfma_f32_16x16x32_bf16 v[24:27], v[164:167], v[168:171], v[24:27]
	v_mfma_f32_16x16x32_bf16 v[12:15], v[164:167], v[194:197], v[12:15]
	v_mfma_f32_16x16x32_bf16 v[16:19], v[172:175], v[168:171], v[16:19]
	v_mfma_f32_16x16x32_bf16 v[20:23], v[172:175], v[194:197], v[20:23]
	s_waitcnt vmcnt(0)
	v_mfma_f32_16x16x32_bf16 v[24:27], v[198:201], v[28:31], v[24:27]
	v_mfma_f32_16x16x32_bf16 v[12:15], v[198:201], v[36:39], v[12:15]
	v_mfma_f32_16x16x32_bf16 v[16:19], v[32:35], v[28:31], v[16:19]
	v_mfma_f32_16x16x32_bf16 v[20:23], v[32:35], v[36:39], v[20:23]
	s_nop 15
	s_nop 15
	v_add_u32_e32 v11, s11, v6
	v_or_b32_e32 v28, s16, v7
	v_lshlrev_b32_e32 v0, 13, v11
	s_nop 1
	ds_write2_b32 v9, v24, v12 offset1:16
	ds_write2_b32 v9, v25, v13 offset0:32 offset1:48
	ds_write2_b32 v9, v26, v14 offset0:64 offset1:80
	ds_write2_b32 v9, v27, v15 offset0:96 offset1:112
	ds_write2_b32 v10, v16, v20 offset1:16
	ds_write2_b32 v10, v17, v21 offset0:32 offset1:48
	ds_write2_b32 v10, v18, v22 offset0:64 offset1:80
	ds_write2_b32 v10, v19, v23 offset0:96 offset1:112
	v_lshl_add_u64 v[12:13], s[38:39], 0, v[0:1]
	v_ashrrev_i32_e32 v29, 31, v28
	v_lshl_add_u64 v[12:13], v[28:29], 2, v[12:13]
	v_add_co_u32_e32 v12, vcc, s9, v12
	s_waitcnt lgkmcnt(0)
	s_nop 0
	v_addc_co_u32_e32 v13, vcc, -1, v13, vcc
	s_barrier
	global_load_dwordx2 v[30:31], v[12:13], off
	ds_read2st64_b64 v[12:15], v8 offset1:8
	ds_read2st64_b64 v[16:19], v8 offset0:32 offset1:40
	ds_read2st64_b64 v[20:23], v8 offset0:16 offset1:24
	ds_read2st64_b64 v[24:27], v8 offset0:48 offset1:56
	v_lshlrev_b32_e32 v0, 12, v11
	v_lshl_add_u64 v[32:33], s[4:5], 0, v[0:1]
	v_lshl_add_u64 v[28:29], v[28:29], 1, v[32:33]
	s_waitcnt lgkmcnt(2)
	v_mov_b32_e32 v32, v16
	v_mov_b32_e32 v33, v12
	v_mov_b32_e32 v34, v18
	v_mov_b32_e32 v35, v14
	v_mov_b32_e32 v12, v17
	v_pk_add_f32 v[16:17], v[32:33], 0 op_sel_hi:[1,0]
	s_waitcnt lgkmcnt(0)
	v_mov_b32_e32 v36, v24
	v_mov_b32_e32 v37, v20
	v_mov_b32_e32 v14, v19
	v_pk_add_f32 v[12:13], v[12:13], 0 op_sel_hi:[1,0]
	v_pk_add_f32 v[16:17], v[16:17], v[34:35]
	v_mov_b32_e32 v38, v26
	v_mov_b32_e32 v39, v22
	v_mov_b32_e32 v20, v25
	v_pk_add_f32 v[12:13], v[12:13], v[14:15]
	v_pk_add_f32 v[14:15], v[16:17], v[36:37]
	v_mov_b32_e32 v22, v27
	v_pk_add_f32 v[12:13], v[12:13], v[20:21]
	v_pk_add_f32 v[14:15], v[14:15], v[38:39]
	s_add_i32 s10, s10, s96
	s_add_i32 s2, s2, s3
	s_add_i32 s6, s6, s7
	v_pk_add_f32 v[12:13], v[12:13], v[22:23]
	s_cmpk_lt_i32 s10, 0x100
	s_waitcnt vmcnt(0)
	v_fmamk_f32 v0, v30, 0x3f9837f0, v15
	v_fmamk_f32 v11, v31, 0x3f9837f0, v13
	v_add_f32_e32 v0, v14, v0
	v_add_f32_e32 v11, v12, v11
	v_cvt_pk_bf16_f32 v0, v0, v11
	global_store_dword v[28:29], v0, off
	s_barrier
	s_cbranch_scc1 .LBB0_1025

; __device__ __forceinline__ f32x4 mfma16(bf16x8 a, bf16x8 b, f32x4 c) { return __builtin_amdgcn_mfma_f32_16x16x32_bf16(a, b, c, 0, 0, 0); }
; template <int MODE>
; __device__ __forceinline__ void skinny_phase(const Params& P, unsigned char* shm) {
;     ...
;         else { A = (const bf16_t*)(ws + O_HFF); Bt = (const bf16_t*)(ws + O_WDT); ld = DFF; nks = 22; k0 = wave * 704; }
;         const bf16_t* ap = A + (size_t)(ROW_S + 32 * mt + l16) * ld + k0 + 8 * q; const bf16_t* bp = Bt + (size_t)(32 * nt + l16) * ld + k0 + 8 * q;
;         f32x4 acc[2][2];
; #pragma unroll
;         for (int i = 0; i < 2; ++i) { acc[i][0] = (f32x4){0.f, 0.f, 0.f, 0.f}; acc[i][1] = (f32x4){0.f, 0.f, 0.f, 0.f}; }
; #pragma unroll 8
;         for (int ks = 0; ks < nks; ++ks) { const bf16x8 a0 = *(const bf16x8*)(ap + 32 * ks), a1 = *(const bf16x8*)(ap + (size_t)16 * ld + 32 * ks), b0 = *(const bf16x8*)(bp + 32 * ks), b1 = *(const bf16x8*)(bp + (size_t)16 * ld + 32 * ks);
;             acc[0][0] = mfma16(a0, b0, acc[0][0]); acc[0][1] = mfma16(a0, b1, acc[0][1]); acc[1][0] = mfma16(a1, b0, acc[1][0]); acc[1][1] = mfma16(a1, b1, acc[1][1]); }
.LBB0_1358:
	s_and_b32 s9, s4, 0x60
	s_bitset1_b32 s9, 13
	v_or_b32_e32 v0, s9, v153
	v_mul_u32_u24_e32 v0, 0x1600, v0
	v_lshlrev_b32_e32 v0, 1, v0
	v_lshl_add_u64 v[56:57], v[2:3], 0, v[0:1]
	s_and_b32 s10, s2, 0xffffffe0
	v_or_b32_e32 v0, s10, v153
	v_mad_i64_i32 v[58:59], s[0:1], v0, s8, v[4:5]
	v_add_co_u32_e32 v60, vcc, 0x2c000, v56
	s_nop 1
	v_addc_co_u32_e32 v61, vcc, 0, v57, vcc
	v_add_co_u32_e32 v62, vcc, 0x2c000, v58
	s_nop 1
	v_addc_co_u32_e32 v63, vcc, 0, v59, vcc
	global_load_dwordx4 v[66:69], v[56:57], off
	global_load_dwordx4 v[70:73], v[58:59], off
	global_load_dwordx4 v[74:77], v[60:61], off
	global_load_dwordx4 v[78:81], v[62:63], off
	global_load_dwordx4 v[82:85], v[56:57], off offset:64
	global_load_dwordx4 v[86:89], v[58:59], off offset:64
	global_load_dwordx4 v[90:93], v[60:61], off offset:64
	global_load_dwordx4 v[94:97], v[62:63], off offset:64
	global_load_dwordx4 v[98:101], v[56:57], off offset:128
	global_load_dwordx4 v[102:105], v[58:59], off offset:128
	global_load_dwordx4 v[106:109], v[60:61], off offset:128
	global_load_dwordx4 v[110:113], v[62:63], off offset:128
	global_load_dwordx4 v[114:117], v[56:57], off offset:192
	global_load_dwordx4 v[118:121], v[58:59], off offset:192
	global_load_dwordx4 v[122:125], v[60:61], off offset:192
	global_load_dwordx4 v[128:131], v[62:63], off offset:192
	global_load_dwordx4 v[132:135], v[56:57], off offset:256
	global_load_dwordx4 v[136:139], v[58:59], off offset:256
	global_load_dwordx4 v[140:143], v[60:61], off offset:256
	global_load_dwordx4 v[144:147], v[62:63], off offset:256
	global_load_dwordx4 v[148:151], v[56:57], off offset:320
	global_load_dwordx4 v[170:173], v[58:59], off offset:320
	global_load_dwordx4 v[174:177], v[60:61], off offset:320
	global_load_dwordx4 v[178:181], v[62:63], off offset:320
	global_load_dwordx4 v[188:191], v[56:57], off offset:384
	global_load_dwordx4 v[192:195], v[58:59], off offset:384
	global_load_dwordx4 v[196:199], v[60:61], off offset:384
	global_load_dwordx4 v[200:203], v[62:63], off offset:384
	global_load_dwordx4 v[204:207], v[56:57], off offset:448
	global_load_dwordx4 v[208:211], v[58:59], off offset:448
	global_load_dwordx4 v[32:35], v[60:61], off offset:448
	global_load_dwordx4 v[36:39], v[62:63], off offset:448
	s_waitcnt vmcnt(28)
	v_mfma_f32_16x16x32_bf16 v[6:9], v[66:69], v[70:73], 0
	v_mfma_f32_16x16x32_bf16 v[20:23], v[66:69], v[78:81], 0
	v_mfma_f32_16x16x32_bf16 v[24:27], v[74:77], v[70:73], 0
	v_mfma_f32_16x16x32_bf16 v[10:13], v[74:77], v[78:81], 0
	global_load_dwordx4 v[66:69], v[56:57], off offset:512
	global_load_dwordx4 v[70:73], v[58:59], off offset:512
	global_load_dwordx4 v[74:77], v[60:61], off offset:512
	global_load_dwordx4 v[78:81], v[62:63], off offset:512
	s_waitcnt vmcnt(28)
	v_mfma_f32_16x16x32_bf16 v[6:9], v[82:85], v[86:89], v[6:9]
	v_mfma_f32_16x16x32_bf16 v[20:23], v[82:85], v[94:97], v[20:23]
	v_mfma_f32_16x16x32_bf16 v[24:27], v[90:93], v[86:89], v[24:27]
	v_mfma_f32_16x16x32_bf16 v[10:13], v[90:93], v[94:97], v[10:13]
	global_load_dwordx4 v[82:85], v[56:57], off offset:576
	global_load_dwordx4 v[86:89], v[58:59], off offset:576
	global_load_dwordx4 v[90:93], v[60:61], off offset:576
	global_load_dwordx4 v[94:97], v[62:63], off offset:576
	s_waitcnt vmcnt(28)
	v_mfma_f32_16x16x32_bf16 v[6:9], v[98:101], v[102:105], v[6:9]
	v_mfma_f32_16x16x32_bf16 v[20:23], v[98:101], v[110:113], v[20:23]
	v_mfma_f32_16x16x32_bf16 v[24:27], v[106:109], v[102:105], v[24:27]
	v_mfma_f32_16x16x32_bf16 v[10:13], v[106:109], v[110:113], v[10:13]
	global_load_dwordx4 v[98:101], v[56:57], off offset:640
	global_load_dwordx4 v[102:105], v[58:59], off offset:640
	global_load_dwordx4 v[106:109], v[60:61], off offset:640
	global_load_dwordx4 v[110:113], v[62:63], off offset:640
	s_waitcnt vmcnt(28)
	v_mfma_f32_16x16x32_bf16 v[6:9], v[114:117], v[118:121], v[6:9]
	v_mfma_f32_16x16x32_bf16 v[20:23], v[114:117], v[128:131], v[20:23]
	v_mfma_f32_16x16x32_bf16 v[24:27], v[122:125], v[118:121], v[24:27]
	v_mfma_f32_16x16x32_bf16 v[10:13], v[122:125], v[128:131], v[10:13]
	global_load_dwordx4 v[114:117], v[56:57], off offset:704
	global_load_dwordx4 v[118:121], v[58:59], off offset:704
	global_load_dwordx4 v[122:125], v[60:61], off offset:704
	global_load_dwordx4 v[128:131], v[62:63], off offset:704
	s_waitcnt vmcnt(28)
	v_mfma_f32_16x16x32_bf16 v[6:9], v[132:135], v[136:139], v[6:9]
	v_mfma_f32_16x16x32_bf16 v[20:23], v[132:135], v[144:147], v[20:23]
	v_mfma_f32_16x16x32_bf16 v[24:27], v[140:143], v[136:139], v[24:27]
	v_mfma_f32_16x16x32_bf16 v[10:13], v[140:143], v[144:147], v[10:13]
	global_load_dwordx4 v[132:135], v[56:57], off offset:768
	global_load_dwordx4 v[136:139], v[58:59], off offset:768
	global_load_dwordx4 v[140:143], v[60:61], off offset:768
	global_load_dwordx4 v[144:147], v[62:63], off offset:768
	s_waitcnt vmcnt(28)
	v_mfma_f32_16x16x32_bf16 v[6:9], v[148:151], v[170:173], v[6:9]
	v_mfma_f32_16x16x32_bf16 v[20:23], v[148:151], v[178:181], v[20:23]
	v_mfma_f32_16x16x32_bf16 v[24:27], v[174:177], v[170:173], v[24:27]
	v_mfma_f32_16x16x32_bf16 v[10:13], v[174:177], v[178:181], v[10:13]
	global_load_dwordx4 v[148:151], v[56:57], off offset:832
	global_load_dwordx4 v[170:173], v[58:59], off offset:832
	global_load_dwordx4 v[174:177], v[60:61], off offset:832
	global_load_dwordx4 v[178:181], v[62:63], off offset:832
	s_waitcnt vmcnt(28)
	v_mfma_f32_16x16x32_bf16 v[6:9], v[188:191], v[192:195], v[6:9]
	v_mfma_f32_16x16x32_bf16 v[20:23], v[188:191], v[200:203], v[20:23]
	v_mfma_f32_16x16x32_bf16 v[24:27], v[196:199], v[192:195], v[24:27]
	v_mfma_f32_16x16x32_bf16 v[10:13], v[196:199], v[200:203], v[10:13]
	global_load_dwordx4 v[188:191], v[56:57], off offset:896
	global_load_dwordx4 v[192:195], v[58:59], off offset:896
	global_load_dwordx4 v[196:199], v[60:61], off offset:896
	global_load_dwordx4 v[200:203], v[62:63], off offset:896
	s_waitcnt vmcnt(28)
; __device__ __forceinline__ f32x4 mfma16(bf16x8 a, bf16x8 b, f32x4 c) { return __builtin_amdgcn_mfma_f32_16x16x32_bf16(a, b, c, 0, 0, 0); }
; #define MFMA_SETTLE() do { __builtin_amdgcn_sched_barrier(0); asm volatile("s_nop 15\n\ts_nop 15" ::: "memory"); __builtin_amdgcn_sched_barrier(0); } while (0)
; template <int MODE>
; __device__ __forceinline__ void skinny_phase(const Params& P, unsigned char* shm) {
;     ...
;         for (int ks = 0; ks < nks; ++ks) { const bf16x8 a0 = *(const bf16x8*)(ap + 32 * ks), a1 = *(const bf16x8*)(ap + (size_t)16 * ld + 32 * ks), b0 = *(const bf16x8*)(bp + 32 * ks), b1 = *(const bf16x8*)(bp + (size_t)16 * ld + 32 * ks);
;             acc[0][0] = mfma16(a0, b0, acc[0][0]); acc[0][1] = mfma16(a0, b1, acc[0][1]); acc[1][0] = mfma16(a1, b0, acc[1][0]); acc[1][1] = mfma16(a1, b1, acc[1][1]); }
;         MFMA_SETTLE();
; #pragma unroll
;         for (int mi = 0; mi < 2; ++mi)
; #pragma unroll
;             for (int ni = 0; ni < 2; ++ni)
; #pragma unroll
;                 for (int r = 0; r < 4; ++r) red[wave * 1024 + (16 * mi + 4 * q + r) * 32 + 16 * ni + l16] = acc[mi][ni][r];
;         __syncthreads();
;         { const int e = tid * 2, rr = e >> 5, cc = e & 31; const int row = ROW_S + 32 * mt + rr, col = 32 * nt + cc;
	v_mfma_f32_16x16x32_bf16 v[6:9], v[204:207], v[208:211], v[6:9]
	v_mfma_f32_16x16x32_bf16 v[20:23], v[204:207], v[36:39], v[20:23]
	v_mfma_f32_16x16x32_bf16 v[24:27], v[32:35], v[208:211], v[24:27]
	v_mfma_f32_16x16x32_bf16 v[10:13], v[32:35], v[36:39], v[10:13]
	global_load_dwordx4 v[204:207], v[56:57], off offset:960
	global_load_dwordx4 v[208:211], v[58:59], off offset:960
	global_load_dwordx4 v[32:35], v[60:61], off offset:960
	global_load_dwordx4 v[36:39], v[62:63], off offset:960
	s_waitcnt vmcnt(28)
	v_mfma_f32_16x16x32_bf16 v[6:9], v[66:69], v[70:73], v[6:9]
	v_mfma_f32_16x16x32_bf16 v[20:23], v[66:69], v[78:81], v[20:23]
	v_mfma_f32_16x16x32_bf16 v[24:27], v[74:77], v[70:73], v[24:27]
	v_mfma_f32_16x16x32_bf16 v[10:13], v[74:77], v[78:81], v[10:13]
	global_load_dwordx4 v[66:69], v[56:57], off offset:1024
	global_load_dwordx4 v[70:73], v[58:59], off offset:1024
	global_load_dwordx4 v[74:77], v[60:61], off offset:1024
	global_load_dwordx4 v[78:81], v[62:63], off offset:1024
	s_waitcnt vmcnt(28)
	v_mfma_f32_16x16x32_bf16 v[6:9], v[82:85], v[86:89], v[6:9]
	v_mfma_f32_16x16x32_bf16 v[20:23], v[82:85], v[94:97], v[20:23]
	v_mfma_f32_16x16x32_bf16 v[24:27], v[90:93], v[86:89], v[24:27]
	v_mfma_f32_16x16x32_bf16 v[10:13], v[90:93], v[94:97], v[10:13]
	global_load_dwordx4 v[82:85], v[56:57], off offset:1088
	global_load_dwordx4 v[86:89], v[58:59], off offset:1088
	global_load_dwordx4 v[90:93], v[60:61], off offset:1088
	global_load_dwordx4 v[94:97], v[62:63], off offset:1088
	s_waitcnt vmcnt(28)
	v_mfma_f32_16x16x32_bf16 v[6:9], v[98:101], v[102:105], v[6:9]
	v_mfma_f32_16x16x32_bf16 v[20:23], v[98:101], v[110:113], v[20:23]
	v_mfma_f32_16x16x32_bf16 v[24:27], v[106:109], v[102:105], v[24:27]
	v_mfma_f32_16x16x32_bf16 v[10:13], v[106:109], v[110:113], v[10:13]
	global_load_dwordx4 v[98:101], v[56:57], off offset:1152
	global_load_dwordx4 v[102:105], v[58:59], off offset:1152
	global_load_dwordx4 v[106:109], v[60:61], off offset:1152
	global_load_dwordx4 v[110:113], v[62:63], off offset:1152
	s_waitcnt vmcnt(28)
	v_mfma_f32_16x16x32_bf16 v[6:9], v[114:117], v[118:121], v[6:9]
	v_mfma_f32_16x16x32_bf16 v[20:23], v[114:117], v[128:131], v[20:23]
	v_mfma_f32_16x16x32_bf16 v[24:27], v[122:125], v[118:121], v[24:27]
	v_mfma_f32_16x16x32_bf16 v[10:13], v[122:125], v[128:131], v[10:13]
	global_load_dwordx4 v[114:117], v[56:57], off offset:1216
	global_load_dwordx4 v[118:121], v[58:59], off offset:1216
	global_load_dwordx4 v[122:125], v[60:61], off offset:1216
	global_load_dwordx4 v[128:131], v[62:63], off offset:1216
	s_waitcnt vmcnt(28)
	v_mfma_f32_16x16x32_bf16 v[6:9], v[132:135], v[136:139], v[6:9]
	v_mfma_f32_16x16x32_bf16 v[20:23], v[132:135], v[144:147], v[20:23]
	v_mfma_f32_16x16x32_bf16 v[24:27], v[140:143], v[136:139], v[24:27]
	v_mfma_f32_16x16x32_bf16 v[10:13], v[140:143], v[144:147], v[10:13]
	global_load_dwordx4 v[132:135], v[56:57], off offset:1280
	global_load_dwordx4 v[136:139], v[58:59], off offset:1280
	global_load_dwordx4 v[140:143], v[60:61], off offset:1280
	global_load_dwordx4 v[144:147], v[62:63], off offset:1280
	s_waitcnt vmcnt(28)
	v_mfma_f32_16x16x32_bf16 v[6:9], v[148:151], v[170:173], v[6:9]
	v_mfma_f32_16x16x32_bf16 v[20:23], v[148:151], v[178:181], v[20:23]
	v_mfma_f32_16x16x32_bf16 v[24:27], v[174:177], v[170:173], v[24:27]
	v_mfma_f32_16x16x32_bf16 v[10:13], v[174:177], v[178:181], v[10:13]
	global_load_dwordx4 v[148:151], v[56:57], off offset:1344
	global_load_dwordx4 v[170:173], v[58:59], off offset:1344
	global_load_dwordx4 v[174:177], v[60:61], off offset:1344
	global_load_dwordx4 v[178:181], v[62:63], off offset:1344
	s_waitcnt vmcnt(28)
	v_mfma_f32_16x16x32_bf16 v[6:9], v[188:191], v[192:195], v[6:9]
	v_mfma_f32_16x16x32_bf16 v[20:23], v[188:191], v[200:203], v[20:23]
	v_mfma_f32_16x16x32_bf16 v[24:27], v[196:199], v[192:195], v[24:27]
	v_mfma_f32_16x16x32_bf16 v[10:13], v[196:199], v[200:203], v[10:13]
	s_waitcnt vmcnt(24)
	v_mfma_f32_16x16x32_bf16 v[6:9], v[204:207], v[208:211], v[6:9]
	v_mfma_f32_16x16x32_bf16 v[20:23], v[204:207], v[36:39], v[20:23]
	v_mfma_f32_16x16x32_bf16 v[24:27], v[32:35], v[208:211], v[24:27]
	v_mfma_f32_16x16x32_bf16 v[10:13], v[32:35], v[36:39], v[10:13]
	s_waitcnt vmcnt(20)
	v_mfma_f32_16x16x32_bf16 v[6:9], v[66:69], v[70:73], v[6:9]
	v_mfma_f32_16x16x32_bf16 v[20:23], v[66:69], v[78:81], v[20:23]
	v_mfma_f32_16x16x32_bf16 v[24:27], v[74:77], v[70:73], v[24:27]
	v_mfma_f32_16x16x32_bf16 v[10:13], v[74:77], v[78:81], v[10:13]
	s_waitcnt vmcnt(16)
	v_mfma_f32_16x16x32_bf16 v[6:9], v[82:85], v[86:89], v[6:9]
	v_mfma_f32_16x16x32_bf16 v[20:23], v[82:85], v[94:97], v[20:23]
	v_mfma_f32_16x16x32_bf16 v[24:27], v[90:93], v[86:89], v[24:27]
	v_mfma_f32_16x16x32_bf16 v[10:13], v[90:93], v[94:97], v[10:13]
	s_waitcnt vmcnt(12)
	v_mfma_f32_16x16x32_bf16 v[6:9], v[98:101], v[102:105], v[6:9]
	v_mfma_f32_16x16x32_bf16 v[20:23], v[98:101], v[110:113], v[20:23]
	v_mfma_f32_16x16x32_bf16 v[24:27], v[106:109], v[102:105], v[24:27]
	v_mfma_f32_16x16x32_bf16 v[10:13], v[106:109], v[110:113], v[10:13]
	s_waitcnt vmcnt(8)
	v_mfma_f32_16x16x32_bf16 v[6:9], v[114:117], v[118:121], v[6:9]
	v_mfma_f32_16x16x32_bf16 v[20:23], v[114:117], v[128:131], v[20:23]
	v_mfma_f32_16x16x32_bf16 v[24:27], v[122:125], v[118:121], v[24:27]
	v_mfma_f32_16x16x32_bf16 v[10:13], v[122:125], v[128:131], v[10:13]
	s_waitcnt vmcnt(4)
	v_mfma_f32_16x16x32_bf16 v[6:9], v[132:135], v[136:139], v[6:9]
	v_mfma_f32_16x16x32_bf16 v[20:23], v[132:135], v[144:147], v[20:23]
	v_mfma_f32_16x16x32_bf16 v[24:27], v[140:143], v[136:139], v[24:27]
	v_mfma_f32_16x16x32_bf16 v[10:13], v[140:143], v[144:147], v[10:13]
	s_waitcnt vmcnt(0)
	v_mfma_f32_16x16x32_bf16 v[6:9], v[148:151], v[170:173], v[6:9]
	v_mfma_f32_16x16x32_bf16 v[20:23], v[148:151], v[178:181], v[20:23]
	v_mfma_f32_16x16x32_bf16 v[24:27], v[174:177], v[170:173], v[24:27]
	v_mfma_f32_16x16x32_bf16 v[10:13], v[174:177], v[178:181], v[10:13]
	s_nop 15
	s_nop 15
	s_nop 5
	ds_write2_b32 v17, v6, v20 offset1:16
	ds_write2_b32 v17, v7, v21 offset0:32 offset1:48
	ds_write2_b32 v17, v8, v22 offset0:64 offset1:80
	ds_write2_b32 v17, v9, v23 offset0:96 offset1:112
	ds_write2_b32 v18, v24, v10 offset1:16
	ds_write2_b32 v18, v25, v11 offset0:32 offset1:48
	ds_write2_b32 v18, v26, v12 offset0:64 offset1:80
	ds_write2_b32 v18, v27, v13 offset0:96 offset1:112
	v_or_b32_e32 v6, s10, v15
	v_add_lshl_u32 v0, s9, v14, 12
	v_ashrrev_i32_e32 v7, 31, v6
	v_lshl_add_u64 v[8:9], s[12:13], 0, v[0:1]
	v_lshlrev_b64 v[28:29], 1, v[6:7]
	v_lshl_add_u64 v[6:7], v[8:9], 0, v[28:29]
	s_waitcnt lgkmcnt(0)
	s_barrier
; __device__ __forceinline__ unsigned cvt_pk_bf16(float lo, float hi) { unsigned r; asm volatile("v_cvt_pk_bf16_f32 %0, %1, %2" : "=v"(r) : "v"(lo), "v"(hi)); return r; }
; __device__ __forceinline__ float bflo(unsigned w) { return __uint_as_float(w << 16); }
; __device__ __forceinline__ float bfhi(unsigned w) { return __uint_as_float(w & 0xffff0000u); }
; __device__ __forceinline__ float sigmoidf_(float x) { return __builtin_amdgcn_rcpf(1.0f + __expf(-x)); }
; template <int MODE>
; __device__ __forceinline__ void skinny_phase(const Params& P, unsigned char* shm) {
;     ...
;         { const int e = tid * 2, rr = e >> 5, cc = e & 31; const int row = ROW_S + 32 * mt + rr, col = 32 * nt + cc;
;           float s0 = 0.f, s1 = 0.f, u0 = 0.f, u1 = 0.f;
; #pragma unroll
;           for (int w = 0; w < 4; ++w) { const f32x2 x = *(const f32x2*)(red + w * 1024 + e), y = *(const f32x2*)(red + (4 + w) * 1024 + e); s0 += x.x; s1 += x.y; u0 += y.x; u1 += y.y; }
;           if (MODE == 0) { const bf16_t* gp = (const bf16_t*)(ws + O_PROJ) + (size_t)row * NPROJ + col;
;               const unsigned ga = *(const unsigned*)(gp + C_GA), gb = *(const unsigned*)(gp + C_GB);
;               const float m0 = sigmoidf_(bflo(ga)) * s0 + sigmoidf_(bflo(gb)) * u0, m1 = sigmoidf_(bfhi(ga)) * s1 + sigmoidf_(bfhi(gb)) * u1;
;               *(unsigned*)((bf16_t*)(ws + O_MIX) + (size_t)row * D + col) = cvt_pk_bf16(m0, m1); }
;           else if (MODE == 1) { const f32x2 xv = *(const f32x2*)(P.in[1] + (size_t)(row - ROW_S) * D + col);
;               *(unsigned*)((bf16_t*)(ws + O_R) + (size_t)row * D + col) = cvt_pk_bf16(ALPHA * xv.x + s0 + u0, ALPHA * xv.y + s1 + u1); }
;           else { const unsigned xw = *(const unsigned*)((const bf16_t*)(ws + O_X1B) + (size_t)row * D + col);
;               *(unsigned*)((bf16_t*)(ws + O_R) + (size_t)row * D + col) = cvt_pk_bf16(ALPHA * bflo(xw) + s0 + u0, ALPHA * bfhi(xw) + s1 + u1); } }
	global_load_dword v19, v[6:7], off
	ds_read2st64_b64 v[6:9], v16 offset1:8
	ds_read2st64_b64 v[10:13], v16 offset0:32 offset1:40
	ds_read2st64_b64 v[20:23], v16 offset0:16 offset1:24
	ds_read2st64_b64 v[24:27], v16 offset0:48 offset1:56
	v_lshl_add_u64 v[30:31], s[6:7], 0, v[0:1]
	v_lshl_add_u64 v[28:29], v[30:31], 0, v[28:29]
	s_waitcnt lgkmcnt(2)
	v_mov_b32_e32 v30, v10
	v_mov_b32_e32 v31, v6
	v_mov_b32_e32 v32, v12
	v_mov_b32_e32 v33, v8
	v_mov_b32_e32 v6, v11
	v_pk_add_f32 v[10:11], v[30:31], 0 op_sel_hi:[1,0]
	s_waitcnt lgkmcnt(0)
	v_mov_b32_e32 v34, v24
	v_mov_b32_e32 v35, v20
	v_mov_b32_e32 v8, v13
	v_pk_add_f32 v[6:7], v[6:7], 0 op_sel_hi:[1,0]
	v_pk_add_f32 v[10:11], v[10:11], v[32:33]
	v_mov_b32_e32 v36, v26
	v_mov_b32_e32 v37, v22
	v_mov_b32_e32 v20, v25
	v_pk_add_f32 v[6:7], v[6:7], v[8:9]
	v_pk_add_f32 v[8:9], v[10:11], v[34:35]
	v_mov_b32_e32 v22, v27
	v_pk_add_f32 v[6:7], v[6:7], v[20:21]
	v_pk_add_f32 v[8:9], v[8:9], v[36:37]
	s_add_i32 s94, s94, s96
	s_add_i32 s2, s2, s3
	s_add_i32 s4, s4, s5
	v_pk_add_f32 v[6:7], v[6:7], v[22:23]
	s_cmpk_lt_i32 s94, 0x100
	s_waitcnt vmcnt(0)
	v_lshlrev_b32_e32 v0, 16, v19
	v_and_b32_e32 v10, 0xffff0000, v19
	v_fmamk_f32 v0, v0, 0x3f9837f0, v9
	v_fmamk_f32 v7, v10, 0x3f9837f0, v7
	v_add_f32_e32 v0, v8, v0
	v_add_f32_e32 v6, v6, v7
	v_cvt_pk_bf16_f32 v0, v0, v6
	global_store_dword v[28:29], v0, off
	s_barrier
	s_cbranch_scc1 .LBB0_1358
